# chain step: seven 64-bit prefetch addresses formed with one v_lshl_add_u64 each (was v_add_co + s_nop + v_addc)
# baseline (speedup 1.0000x reference)
.LBB0_155:
	s_and_b64 vcc, exec, s[40:41]
	s_cbranch_vccz .LBB0_174
	s_cmp_gt_i32 s21, 1
	s_mov_b64 s[22:23], -1
	s_cbranch_scc0 .LBB0_172
	s_mov_b32 s25, s13
	s_mov_b32 s35, s16
	s_cmpk_gt_i32 s20, 0xff
	s_cbranch_scc1 .LBB0_171
	s_mov_b64 s[100:101], 0x1000
	v_lshlrev_b32_e32 v112, 4, v134
	v_mov_b32_e32 v113, v1
	s_waitcnt vmcnt(0)
	v_lshl_add_u64 v[2:3], s[94:95], 0, v[112:113]
	s_mov_b64 s[6:7], 0x4800000
	v_lshl_add_u64 v[114:115], v[2:3], 0, s[6:7]
	s_mov_b64 s[6:7], 0xb400000
	v_lshl_add_u64 v[116:117], v[2:3], 0, s[6:7]
	s_mov_b64 s[6:7], 0xd800000
	v_lshl_add_u64 v[118:119], v[2:3], 0, s[6:7]
	v_lshrrev_b32_e32 v0, 3, v134
	v_lshlrev_b32_e32 v2, 3, v134
	v_mul_lo_u32 v0, v0, s96
	v_and_b32_e32 v2, 56, v2
	v_or_b32_e32 v0, v0, v2
	v_lshlrev_b32_e32 v120, 1, v0
	v_add_u32_e32 v0, 0x100, v134
	v_lshrrev_b32_e32 v3, 3, v0
	v_ashrrev_i32_e32 v0, 4, v0
	v_lshlrev_b32_e32 v9, 8, v0
	v_xor_b32_e32 v0, v0, v134
	v_lshlrev_b32_e32 v0, 4, v0
	v_and_b32_e32 v10, 0xf0, v0
	v_add_u32_e32 v0, 0x200, v134
	v_mul_lo_u32 v3, v3, s96
	v_ashrrev_i32_e32 v0, 4, v0
	v_or_b32_e32 v2, v3, v2
	v_lshlrev_b32_e32 v11, 8, v0
	v_xor_b32_e32 v0, v0, v134
	v_lshlrev_b32_e32 v122, 1, v2
	v_lshlrev_b32_e32 v2, 2, v134
	v_lshlrev_b32_e32 v0, 4, v0
	v_ashrrev_i32_e32 v3, 31, v2
	v_and_b32_e32 v12, 0xf0, v0
	v_add_u32_e32 v0, 0x300, v134
	v_and_b32_e32 v110, 15, v134
	v_lshl_add_u64 v[2:3], v[2:3], 2, s[94:95]
	s_mov_b64 s[6:7], 0xfd20000
	v_ashrrev_i32_e32 v0, 4, v0
	v_bfe_u32 v5, v134, 1, 3
	v_lshrrev_b32_e32 v6, 4, v134
	v_bfe_u32 v7, v134, 4, 2
	v_ashrrev_i32_e32 v8, 6, v134
	v_lshl_add_u64 v[124:125], v[2:3], 0, s[6:7]
	v_ashrrev_i32_e32 v2, 4, v134
	v_lshlrev_b32_e32 v13, 8, v0
	v_xor_b32_e32 v0, v0, v134
	v_lshlrev_b32_e32 v111, 7, v110
	v_lshlrev_b32_e32 v3, 8, v2
	v_xor_b32_e32 v2, v2, v134
	v_lshlrev_b32_e32 v0, 4, v0
	v_lshl_or_b32 v113, v8, 11, v111
	v_lshlrev_b32_e32 v126, 4, v8
	v_bitop3_b32 v8, v6, v5, 3 bitop3:0x6c
	v_bitop3_b32 v5, v7, v5, 4 bitop3:0x36
	v_bfe_u32 v6, v6, 1, 1
	v_lshrrev_b32_e32 v4, 1, v134
	v_lshlrev_b32_e32 v2, 4, v2
	v_and_b32_e32 v14, 0xf0, v0
	s_movk_i32 s6, 0x70
	v_lshlrev_b32_e32 v0, 2, v7
	v_lshlrev_b32_e32 v135, 4, v7
	v_lshlrev_b32_e32 v136, 4, v8
	v_lshlrev_b32_e32 v137, 4, v5
	v_add_u32_e32 v5, v111, v111
	v_bitop3_b32 v7, v6, v134, 15 bitop3:0x78
	v_bitop3_b32 v8, v6, v110, 2 bitop3:0x36
	v_bitop3_b32 v17, v6, v110, 4 bitop3:0x36
	v_bitop3_b32 v18, v6, v110, 6 bitop3:0x36
	v_bitop3_b32 v19, v6, v110, 8 bitop3:0x36
	v_bitop3_b32 v20, v6, v110, 10 bitop3:0x36
	v_bitop3_b32 v21, v6, v110, 12 bitop3:0x36
	v_bitop3_b32 v6, v6, v110, 14 bitop3:0x36
	s_add_u32 s4, s94, 0x6c00000
	v_and_b32_e32 v2, 0xf0, v2
	v_and_b32_e32 v15, 0xffffff80, v112
	v_bitop3_b32 v16, v112, s6, v134 bitop3:0x48
	v_and_b32_e32 v4, 8, v4
	v_lshl_add_u32 v7, v7, 4, v5
	v_lshl_add_u32 v8, v8, 4, v5
	v_lshl_add_u32 v17, v17, 4, v5
	v_lshl_add_u32 v18, v18, 4, v5
	v_lshl_add_u32 v19, v19, 4, v5
	v_lshl_add_u32 v20, v20, 4, v5
	v_lshl_add_u32 v21, v21, 4, v5
	v_lshl_add_u32 v5, v6, 4, v5
	s_addc_u32 s5, s95, 0
	v_mov_b32_e32 v121, v1
	v_mov_b32_e32 v123, v1
	v_cmp_gt_i32_e64 s[38:39], 32, v134
	v_ashrrev_i32_e32 v127, 31, v126
	v_lshlrev_b32_e32 v128, 1, v0
	v_add_u32_e32 v138, v3, v2
	v_add_u32_e32 v139, v9, v10
	v_add_u32_e32 v140, v11, v12
	v_add_u32_e32 v141, v13, v14
	v_add_u32_e32 v142, v15, v16
	v_add_u32_e32 v143, v7, v4
	v_add_u32_e32 v144, v8, v4
	v_add_u32_e32 v145, v17, v4
	v_add_u32_e32 v146, v18, v4
	v_add_u32_e32 v147, v19, v4
	v_add_u32_e32 v148, v20, v4
	v_add_u32_e32 v149, v21, v4
	v_add_u32_e32 v150, v5, v4
	s_and_b32 s6, s20, 7
	s_lshl_b32 s6, s6, 5
	s_lshr_b32 s7, s20, 3
	s_or_b32 s6, s6, s7
	s_branch .LBB0_160

.LBB0_165:
	v_add_u32_e32 v151, v113, v136
	v_add_u32_e32 v129, v111, v136
	v_add_u32_e32 v152, v113, v137
	ds_read_b128 v[106:109], v151 offset:40960
	ds_read_b128 v[102:105], v152 offset:40960
	v_add_u32_e32 v0, v111, v137
	ds_read_b128 v[154:157], v129 offset:32768
	ds_read_b128 v[158:161], v129 offset:34816
	ds_read_b128 v[162:165], v0 offset:32768
	ds_read_b128 v[166:169], v0 offset:34816
	ds_read_b128 v[174:177], v129 offset:36864
	ds_read_b128 v[178:181], v129 offset:38912
	ds_read_b128 v[204:207], v0 offset:36864
	ds_read_b128 v[208:211], v0 offset:38912
	ds_read_b64 v[212:213], v143
	ds_read_b64 v[214:215], v144
	ds_read_b64 v[200:201], v143 offset:4096
	ds_read_b64 v[202:203], v144 offset:4096
	s_add_i32 s11, s12, 1
	s_cmp_lt_u32 s12, 3
	s_cselect_b32 s13, 3, 39
	s_add_i32 s13, s13, s10
	s_and_b64 s[14:15], s[22:23], exec
	s_cselect_b32 s13, s11, s13
	s_add_i32 s14, s13, s7
	s_ashr_i32 s15, s14, 31
	s_lshl_b64 s[14:15], s[14:15], 3
	s_or_b64 s[28:29], s[14:15], s[26:27]
	s_lshl_b64 s[18:19], s[28:29], 14
	v_lshl_add_u64 v[62:63], v[114:115], 0, s[18:19]
	v_lshl_add_u64 v[78:79], v[116:117], 0, s[18:19]
	s_lshl_b32 s16, s13, 6
	s_lshl_b64 s[14:15], s[28:29], 13
	s_ashr_i32 s17, s16, 31
	v_lshl_add_u64 v[86:87], v[118:119], 0, s[14:15]
	s_lshl_b64 s[14:15], s[16:17], 1
	s_add_u32 s14, s8, s14
	s_addc_u32 s15, s9, s15
	v_lshl_add_u64 v[58:59], v[62:63], 0, s[100:101]
	v_lshl_add_u64 v[74:75], v[78:79], 0, s[100:101]
	v_lshl_add_u64 v[90:91], v[86:87], 0, s[100:101]
	v_lshl_add_u64 v[64:65], v[58:59], 0, s[100:101]
	v_lshl_add_u64 v[80:81], v[74:75], 0, s[100:101]
	v_lshl_add_u64 v[66:67], v[64:65], 0, s[100:101]
	v_lshl_add_u64 v[82:83], v[80:81], 0, s[100:101]
	v_lshl_add_u64 v[94:95], s[14:15], 0, v[120:121]
	v_lshl_add_u64 v[98:99], s[14:15], 0, v[122:123]
	global_load_dwordx4 v[54:57], v[62:63], off
	s_nop 0
	global_load_dwordx4 v[58:61], v[58:59], off
	s_nop 0
	global_load_dwordx4 v[62:65], v[64:65], off
	s_nop 0
	global_load_dwordx4 v[66:69], v[66:67], off
	s_nop 0
	global_load_dwordx4 v[70:73], v[78:79], off
	s_nop 0
	global_load_dwordx4 v[74:77], v[74:75], off
	s_nop 0
	global_load_dwordx4 v[78:81], v[80:81], off
	s_nop 0
	global_load_dwordx4 v[82:85], v[82:83], off
	s_nop 0
	global_load_dwordx4 v[86:89], v[86:87], off
	s_nop 0
	global_load_dwordx4 v[90:93], v[90:91], off
	s_nop 0
	global_load_dwordx4 v[94:97], v[94:95], off
	s_nop 0
	global_load_dwordx4 v[98:101], v[98:99], off
	s_and_saveexec_b64 s[40:41], s[38:39]
	s_cbranch_execz .LBB0_167
	s_lshl_b64 s[14:15], s[28:29], 9
	v_lshl_add_u64 v[2:3], v[124:125], 0, s[14:15]
	global_load_dwordx4 v[2:5], v[2:3], off
